# PH2: KVUP mini tasks and x0 tasks assigned by bx (light SLOC workgroups) instead of vcu
# baseline (speedup 1.0000x reference)
; #define LAS __attribute__((address_space(3)))
; template <int KIND>
; __device__ __forceinline__ void mini_task(const Ptrs& P, const bf16* A, int lda, const bf16* B, int ldb, int K, int row0, int cb, LAS unsigned char* lds) {
;     const int tid = threadIdx.x, wave = __builtin_amdgcn_readfirstlane(tid >> 6), lane = tid & 63, r32 = lane & 31, hi = lane >> 5;
;     const int kw = K >> 3;
;     const bf16* ap = A + (size_t)r32 * lda + wave * kw + hi * 8; const bf16* bp = B + (size_t)r32 * ldb + wave * kw + hi * 8;
;     const int erow = row0 + (tid >> 4); const bool emeta = row0 >= MTOK;
;     float e_rs = 0.f; f32x4 e_cs0 = {}, e_cs1 = {};
;     if constexpr (KIND == MK_KVUP) e_rs = P.ssq_kv_()[erow]; else e_rs = P.rs1_()[erow];
;     if constexpr (KIND == MK_KR) { const int epos = emeta ? ((tid >> 4) < NMETA ? (tid >> 4) : 0) : NMETA + (erow & 4095); const int ejp = (tid & 15) >> 1;
; __global__ void __launch_bounds__(NWAVES * 64, 2) hybrid_fwd(Args args) {
;     ...
;     if (IN(2)) for (int rep2_ = 0; rep2_ < 1 + PROBE_CNT(2); ++rep2_) {
;         __syncthreads();
;         for (int tk = vcu; tk < 64; tk += G) mini_task<MK_KVUP>(P, P.kvlat_() + (size_t)MTOK * 512, 512, P.wkv_() + (size_t)tk * 64 * 512, 512, 512, MTOK, tk, lds);
;         for (int pc = 0; pc < 8; ++pc) if ((64 + pc) % G == vcu) { const int e = pc * 512 + tid, g = e >> 6, n = e & 63; float xr = 0.f, xi = 0.f;
.LBB0_405:
	s_cmp_lt_i32 s90, 3
	s_cselect_b64 s[4:5], -1, 0
	s_and_b64 s[18:19], s[4:5], s[0:1]
	v_writelane_b32 v244, s84, 25
	s_andn2_b64 vcc, exec, s[18:19]
	s_nop 0
	v_writelane_b32 v244, s85, 26
	s_cbranch_vccnz .LBB0_539
	v_and_b32_e32 v151, 15, v0
	s_cmp_gt_i32 s2, 63
	v_lshrrev_b32_e32 v64, 5, v0
	v_lshrrev_b32_e32 v34, 4, v0
	v_lshlrev_b32_e32 v35, 2, v151
	s_barrier
	s_cbranch_scc1 .LBB0_411
	v_and_b32_e32 v6, 31, v0
	v_and_b32_e32 v7, 1, v64
	v_lshlrev_b32_e32 v36, 10, v6
	v_mov_b32_e32 v37, 0
	v_lshl_add_u64 v[2:3], s[86:87], 0, v[36:37]
	v_lshlrev_b32_e32 v4, 4, v7
	v_mov_b32_e32 v5, v37
	v_lshl_add_u64 v[2:3], v[2:3], 0, v[4:5]
	s_mov_b64 s[0:1], 0x8e00000
	v_lshl_add_u64 v[38:39], v[2:3], 0, s[0:1]
	v_lshlrev_b32_e32 v2, 2, v34
	v_mov_b32_e32 v3, v37
	v_lshl_add_u64 v[2:3], s[86:87], 0, v[2:3]
	s_mov_b64 s[0:1], 0x28000
	v_lshl_add_u64 v[40:41], v[2:3], 0, s[0:1]
	v_lshlrev_b32_e32 v2, 10, v7
	v_lshlrev_b32_e32 v3, 2, v6
	v_add3_u32 v44, 0, v2, v3
	s_ashr_i32 s97, s96, 31
	v_lshrrev_b32_e32 v2, 1, v0
	s_mov_b32 s98, s2
	s_mov_b32 s99, 0
	s_lshl_b64 s[4:5], s[98:99], 16
	v_and_b32_e32 v2, 16, v2
	v_or3_b32 v2, s4, v36, v2
	v_mov_b32_e32 v3, s5
	s_movk_i32 s0, 0x100
	v_lshl_add_u32 v4, v34, 8, 0
	v_lshlrev_b32_e32 v5, 4, v151
	v_lshl_add_u64 v[2:3], s[86:87], 0, v[2:3]
	s_mov_b64 s[4:5], 0x2000000
	s_ashr_i32 s93, s92, 31
	v_cmp_gt_u32_e64 s[0:1], s0, v0
	v_lshl_add_u64 v[42:43], v[2:3], 0, s[4:5]
	s_lshl_b64 s[6:7], s[92:93], 16
	s_lshl_b32 s3, s2, 6
	s_lshl_b32 s4, s92, 6
	v_add_u32_e32 v45, v4, v5
	v_mov_b32_e32 v46, 0x358637bd
	s_mov_b32 s5, 0x800000
	s_mov_b32 s10, 0xc100000
	s_mov_b32 s11, s2
	s_branch .LBB0_409

; __global__ void __launch_bounds__(NWAVES * 64, 2) hybrid_fwd(Args args) {
;     ...
;         for (int pc = 0; pc < 8; ++pc) if ((64 + pc) % G == vcu) { const int e = pc * 512 + tid, g = e >> 6, n = e & 63; float xr = 0.f, xi = 0.f;
;             for (int s = 0; s < NMETA; ++s) { const f32x2 a = P.apow_()[((size_t)g * 17 + (15 - s)) * 64 + n]; float br = 0.f, bi = 0.f;
;                 for (int q = 0; q < 16; ++q) { const f32x2 w = P.bbar_()[((size_t)g * 64 + n) * 16 + q]; const float uu = P.umeta_()[s * 1024 + g * 16 + q]; br += w.x * uu; bi += w.y * uu; }
;                 xr += a.x * br - a.y * bi; xi += a.x * bi + a.y * br; }
;             P.x0_()[e] = (f32x2){xr, xi}; }
.LBB0_413:
	s_or_b32 s16, s4, 64
	s_mul_hi_u32 s17, s16, s5
	s_mul_i32 s17, s17, s3
	s_sub_i32 s16, s16, s17
	s_sub_i32 s17, s16, s3
	s_cmp_ge_u32 s16, s3
	s_cselect_b32 s16, s17, s16
	s_sub_i32 s17, s16, s3
	s_cmp_ge_u32 s16, s3
	s_cselect_b32 s16, s17, s16
	s_cmp_lg_u32 s16, s2
	s_cbranch_scc1 .LBB0_412
	v_lshl_or_b32 v44, s4, 9, v0
	v_lshrrev_b32_e32 v36, 6, v44
	v_lshlrev_b64 v[2:3], 13, v[36:37]
	v_lshl_add_u64 v[30:31], v[38:39], 0, v[2:3]
	global_load_dwordx4 v[2:5], v[30:31], off offset:112
	global_load_dwordx4 v[6:9], v[30:31], off offset:96
	global_load_dwordx4 v[10:13], v[30:31], off offset:80
	global_load_dwordx4 v[14:17], v[30:31], off offset:64
	global_load_dwordx4 v[18:21], v[30:31], off offset:48
	global_load_dwordx4 v[22:25], v[30:31], off offset:32
	global_load_dwordx4 v[26:29], v[30:31], off
	s_nop 0
	global_load_dwordx4 v[30:33], v[30:31], off offset:16
	v_mov_b32_e32 v46, 0
	s_mov_b32 s16, 16
	v_mov_b64_e32 v[48:49], v[40:41]
	v_mov_b64_e32 v[50:51], v[42:43]
	v_mov_b32_e32 v47, v46
	s_waitcnt vmcnt(7)
	v_mov_b32_e32 v52, v2
	v_mov_b32_e32 v53, v4
	s_waitcnt vmcnt(6)
	v_mov_b32_e32 v54, v6
	v_mov_b32_e32 v55, v8
	s_waitcnt vmcnt(5)
	v_mov_b32_e32 v56, v10
	v_mov_b32_e32 v57, v12
	s_waitcnt vmcnt(4)
	v_mov_b32_e32 v58, v14
	v_mov_b32_e32 v59, v16
	s_waitcnt vmcnt(3)
	v_mov_b32_e32 v60, v18
	v_mov_b32_e32 v61, v20
	s_waitcnt vmcnt(2)
	v_mov_b32_e32 v62, v22
	v_mov_b32_e32 v63, v24
	v_mov_b32_e32 v4, v3
	v_mov_b32_e32 v8, v7
	v_mov_b32_e32 v12, v11
	v_mov_b32_e32 v16, v15
	v_mov_b32_e32 v20, v19
	v_mov_b32_e32 v24, v23
